# EpiGU H stores write-through (sc1) so they do not displace the A/B tiles in the XCD L2
# speedup vs baseline: 1.0272x; 1.0038x over previous
; #define LAS __attribute__((address_space(3)))
; __device__ __forceinline__ float siluf_(float x) { return x * sigmoidf_(x); }
; __device__ __forceinline__ void rows_rstd(LAS unsigned char* sl, int rl0, int fq, float (&rs)[8]) {
;     f32x4 v[8];
; #pragma unroll
;     for (int i = 0; i < 8; ++i) v[i] = *(const LAS f32x4*)(sl + (rl0 + (i >> 2) * 128 + (i & 3) * 16) * 64 + fq * 16);
; #pragma unroll
;     for (int i = 0; i < 8; ++i) { float s = (v[i].x + v[i].y) + (v[i].z + v[i].w); s += __shfl_xor(s, 16); s += __shfl_xor(s, 32); rs[i] = rsqrtf(s * (1.0f / DM) + EPS); }
; }
;     __device__ __forceinline__ void operator()(const f32x4 (&acc)[2][2][4][2], const pg8::Unit& u, int wr, int wc, int fr, int fq) const {
;         const int row0 = u.pm * 256 + wr * 64 + fr, col0 = u.pn * 128 + wc * 32 + 8 * fq;
;         float rs[8]; rows_rstd(sl, wr * 64 + fr, fq, rs);
; #pragma unroll
;         for (int ai = 0; ai < 2; ++ai)
; #pragma unroll
;             for (int m = 0; m < 4; ++m) {
;                 const int row = row0 + ai * 128 + m * 16; const float r = rs[ai * 4 + m];
;                 float h[8];
; #pragma unroll
;                 for (int n = 0; n < 2; ++n)
; #pragma unroll
;                     for (int j = 0; j < 4; ++j) { const float g = acc[ai][0][m][n][j] * r, up = acc[ai][1][m][n][j] * r; h[n * 4 + j] = siluf_(g) * up; }
.LBB0_1652:
	v_xor_b32_e32 v130, 16, v175
	v_xor_b32_e32 v131, 32, v175
	ds_read_b128 v[200:203], v198
	ds_read_b128 v[204:207], v198 offset:1024
	ds_read_b128 v[208:211], v198 offset:2048
	ds_read_b128 v[212:215], v198 offset:3072
	ds_read_b128 v[216:219], v198 offset:8192
	ds_read_b128 v[220:223], v198 offset:9216
	ds_read_b128 v[224:227], v198 offset:10240
	ds_read_b128 v[228:231], v198 offset:11264
	v_lshlrev_b32_e32 v130, 2, v130
	v_lshlrev_b32_e32 v131, 2, v131
	v_mov_b32_e32 v128, 1.0
	v_mov_b32_e32 v129, 1.0
	v_mov_b32_e32 v134, 0xbfb8aa3b
	v_mov_b32_e32 v135, 0x3a800000
	v_add_u32_e32 v132, s45, v163
	v_mul_u32_u24_e32 v132, 0x1600, v132
	v_lshl_or_b32 v133, s38, 7, v171
	v_lshl_add_u32 v132, v133, 1, v132
	s_waitcnt lgkmcnt(0)
	v_add_f32_e32 v232, v200, v201
	v_add_f32_e32 v233, v204, v205
	v_add_f32_e32 v234, v208, v209
	v_add_f32_e32 v235, v212, v213
	v_add_f32_e32 v236, v216, v217
	v_add_f32_e32 v237, v220, v221
	v_add_f32_e32 v238, v224, v225
	v_add_f32_e32 v239, v228, v229
	v_add_f32_e32 v240, v202, v203
	v_add_f32_e32 v241, v206, v207
	v_add_f32_e32 v242, v210, v211
	v_add_f32_e32 v243, v214, v215
	v_add_f32_e32 v244, v218, v219
	v_add_f32_e32 v245, v222, v223
	v_add_f32_e32 v246, v226, v227
	v_add_f32_e32 v247, v230, v231
	v_add_f32_e32 v232, v232, v240
	v_add_f32_e32 v233, v233, v241
	v_add_f32_e32 v234, v234, v242
	v_add_f32_e32 v235, v235, v243
	v_add_f32_e32 v236, v236, v244
	v_add_f32_e32 v237, v237, v245
	v_add_f32_e32 v238, v238, v246
	v_add_f32_e32 v239, v239, v247
	ds_bpermute_b32 v240, v130, v232
	ds_bpermute_b32 v241, v130, v233
	ds_bpermute_b32 v242, v130, v234
	ds_bpermute_b32 v243, v130, v235
	ds_bpermute_b32 v244, v130, v236
	ds_bpermute_b32 v245, v130, v237
	ds_bpermute_b32 v246, v130, v238
	ds_bpermute_b32 v247, v130, v239
	s_waitcnt lgkmcnt(0)
	v_add_f32_e32 v232, v232, v240
	v_add_f32_e32 v233, v233, v241
	v_add_f32_e32 v234, v234, v242
	v_add_f32_e32 v235, v235, v243
	v_add_f32_e32 v236, v236, v244
	v_add_f32_e32 v237, v237, v245
	v_add_f32_e32 v238, v238, v246
	v_add_f32_e32 v239, v239, v247
	ds_bpermute_b32 v240, v131, v232
	ds_bpermute_b32 v241, v131, v233
	ds_bpermute_b32 v242, v131, v234
	ds_bpermute_b32 v243, v131, v235
	ds_bpermute_b32 v244, v131, v236
	ds_bpermute_b32 v245, v131, v237
	ds_bpermute_b32 v246, v131, v238
	ds_bpermute_b32 v247, v131, v239
	s_waitcnt lgkmcnt(0)
	v_add_f32_e32 v232, v232, v240
	v_add_f32_e32 v233, v233, v241
	v_add_f32_e32 v234, v234, v242
	v_add_f32_e32 v235, v235, v243
	v_add_f32_e32 v236, v236, v244
	v_add_f32_e32 v237, v237, v245
	v_add_f32_e32 v238, v238, v246
	v_add_f32_e32 v239, v239, v247
	v_fmaak_f32 v232, v135, v232, 0x358637bd
	v_fmaak_f32 v233, v135, v233, 0x358637bd
	v_fmaak_f32 v234, v135, v234, 0x358637bd
	v_fmaak_f32 v235, v135, v235, 0x358637bd
	v_fmaak_f32 v236, v135, v236, 0x358637bd
	v_fmaak_f32 v237, v135, v237, 0x358637bd
	v_fmaak_f32 v238, v135, v238, 0x358637bd
	v_fmaak_f32 v239, v135, v239, 0x358637bd
	v_rsq_f32_e32 v200, v232
	v_rsq_f32_e32 v202, v233
	v_rsq_f32_e32 v204, v234
	v_rsq_f32_e32 v206, v235
	v_rsq_f32_e32 v208, v236
	v_rsq_f32_e32 v210, v237
	v_rsq_f32_e32 v212, v238
	v_rsq_f32_e32 v214, v239
	s_nop 0
	v_pk_mul_f32 v[124:125], v[124:125], v[200:201] op_sel_hi:[1,0]
	v_pk_mul_f32 v[126:127], v[126:127], v[200:201] op_sel_hi:[1,0]
	v_pk_mul_f32 v[116:117], v[116:117], v[200:201] op_sel_hi:[1,0]
	v_pk_mul_f32 v[118:119], v[118:119], v[200:201] op_sel_hi:[1,0]
	v_pk_mul_f32 v[108:109], v[108:109], v[202:203] op_sel_hi:[1,0]
	v_pk_mul_f32 v[110:111], v[110:111], v[202:203] op_sel_hi:[1,0]
	v_pk_mul_f32 v[100:101], v[100:101], v[202:203] op_sel_hi:[1,0]
	v_pk_mul_f32 v[102:103], v[102:103], v[202:203] op_sel_hi:[1,0]
	v_pk_mul_f32 v[120:121], v[120:121], v[200:201] op_sel_hi:[1,0]
	v_pk_mul_f32 v[122:123], v[122:123], v[200:201] op_sel_hi:[1,0]
	v_pk_mul_f32 v[112:113], v[112:113], v[200:201] op_sel_hi:[1,0]
	v_pk_mul_f32 v[114:115], v[114:115], v[200:201] op_sel_hi:[1,0]
	v_pk_mul_f32 v[104:105], v[104:105], v[202:203] op_sel_hi:[1,0]
	v_pk_mul_f32 v[106:107], v[106:107], v[202:203] op_sel_hi:[1,0]
	v_pk_mul_f32 v[96:97], v[96:97], v[202:203] op_sel_hi:[1,0]
	v_pk_mul_f32 v[98:99], v[98:99], v[202:203] op_sel_hi:[1,0]
	v_pk_mul_f32 v[120:121], v[124:125], v[120:121]
	v_pk_mul_f32 v[122:123], v[126:127], v[122:123]
	v_pk_mul_f32 v[112:113], v[116:117], v[112:113]
	v_pk_mul_f32 v[114:115], v[118:119], v[114:115]
	v_pk_mul_f32 v[104:105], v[108:109], v[104:105]
	v_pk_mul_f32 v[106:107], v[110:111], v[106:107]
	v_pk_mul_f32 v[96:97], v[100:101], v[96:97]
	v_pk_mul_f32 v[98:99], v[102:103], v[98:99]
	v_pk_mul_f32 v[124:125], v[124:125], v[134:135] op_sel_hi:[1,0]
	v_pk_mul_f32 v[126:127], v[126:127], v[134:135] op_sel_hi:[1,0]
	v_pk_mul_f32 v[116:117], v[116:117], v[134:135] op_sel_hi:[1,0]
	v_pk_mul_f32 v[118:119], v[118:119], v[134:135] op_sel_hi:[1,0]
	v_pk_mul_f32 v[108:109], v[108:109], v[134:135] op_sel_hi:[1,0]
	v_pk_mul_f32 v[110:111], v[110:111], v[134:135] op_sel_hi:[1,0]
	v_pk_mul_f32 v[100:101], v[100:101], v[134:135] op_sel_hi:[1,0]
	v_pk_mul_f32 v[102:103], v[102:103], v[134:135] op_sel_hi:[1,0]
	v_exp_f32_e32 v124, v124
	v_exp_f32_e32 v125, v125
	v_exp_f32_e32 v126, v126
	v_exp_f32_e32 v127, v127
	v_exp_f32_e32 v116, v116
	v_exp_f32_e32 v117, v117
	v_exp_f32_e32 v118, v118
	v_exp_f32_e32 v119, v119
	v_exp_f32_e32 v108, v108
	v_exp_f32_e32 v109, v109
	v_exp_f32_e32 v110, v110
	v_exp_f32_e32 v111, v111
	v_exp_f32_e32 v100, v100
	v_exp_f32_e32 v101, v101
	v_exp_f32_e32 v102, v102
	v_exp_f32_e32 v103, v103
	v_pk_add_f32 v[124:125], v[124:125], v[128:129]
	v_pk_add_f32 v[126:127], v[126:127], v[128:129]
; __device__ __forceinline__ unsigned pk2(float lo, float hi) { return pg8::cvt_pk_bf16(lo, hi); }
; __device__ __forceinline__ float siluf_(float x) { return x * sigmoidf_(x); }
;     __device__ __forceinline__ void operator()(const f32x4 (&acc)[2][2][4][2], const pg8::Unit& u, int wr, int wc, int fr, int fq) const {
;     ...
;             for (int m = 0; m < 4; ++m) {
;                 const int row = row0 + ai * 128 + m * 16; const float r = rs[ai * 4 + m];
;                 float h[8];
; #pragma unroll
;                 for (int n = 0; n < 2; ++n)
; #pragma unroll
;                     for (int j = 0; j < 4; ++j) { const float g = acc[ai][0][m][n][j] * r, up = acc[ai][1][m][n][j] * r; h[n * 4 + j] = siluf_(g) * up; }
;                 u32x4 w; w.x = pk2(h[0], h[1]); w.y = pk2(h[2], h[3]); w.z = pk2(h[4], h[5]); w.w = pk2(h[6], h[7]);
;                 *(u32x4*)(H + (size_t)row * FF + col0) = w;
	v_pk_add_f32 v[116:117], v[116:117], v[128:129]
	v_pk_add_f32 v[118:119], v[118:119], v[128:129]
	v_pk_add_f32 v[108:109], v[108:109], v[128:129]
	v_pk_add_f32 v[110:111], v[110:111], v[128:129]
	v_pk_add_f32 v[100:101], v[100:101], v[128:129]
	v_pk_add_f32 v[102:103], v[102:103], v[128:129]
	v_rcp_f32_e32 v124, v124
	v_rcp_f32_e32 v125, v125
	v_rcp_f32_e32 v126, v126
	v_rcp_f32_e32 v127, v127
	v_rcp_f32_e32 v116, v116
	v_rcp_f32_e32 v117, v117
	v_rcp_f32_e32 v118, v118
	v_rcp_f32_e32 v119, v119
	v_rcp_f32_e32 v108, v108
	v_rcp_f32_e32 v109, v109
	v_rcp_f32_e32 v110, v110
	v_rcp_f32_e32 v111, v111
	v_rcp_f32_e32 v100, v100
	v_rcp_f32_e32 v101, v101
	v_rcp_f32_e32 v102, v102
	v_rcp_f32_e32 v103, v103
	v_pk_mul_f32 v[120:121], v[120:121], v[124:125]
	v_pk_mul_f32 v[122:123], v[122:123], v[126:127]
	v_pk_mul_f32 v[112:113], v[112:113], v[116:117]
	v_pk_mul_f32 v[114:115], v[114:115], v[118:119]
	v_pk_mul_f32 v[104:105], v[104:105], v[108:109]
	v_pk_mul_f32 v[106:107], v[106:107], v[110:111]
	v_pk_mul_f32 v[96:97], v[96:97], v[100:101]
	v_pk_mul_f32 v[98:99], v[98:99], v[102:103]
	v_cvt_pk_bf16_f32 v124, v120, v121
	v_cvt_pk_bf16_f32 v125, v122, v123
	v_cvt_pk_bf16_f32 v126, v112, v113
	v_cvt_pk_bf16_f32 v127, v114, v115
	v_cvt_pk_bf16_f32 v108, v104, v105
	v_cvt_pk_bf16_f32 v109, v106, v107
	v_cvt_pk_bf16_f32 v110, v96, v97
	v_cvt_pk_bf16_f32 v111, v98, v99
	v_mov_b32_e32 v136, v132
	global_store_dwordx4 v136, v[124:127], s[8:9] sc1
	v_add_u32_e32 v137, 0x16000, v132
	global_store_dwordx4 v137, v[108:111], s[8:9] sc1
	v_pk_mul_f32 v[92:93], v[92:93], v[204:205] op_sel_hi:[1,0]
	v_pk_mul_f32 v[94:95], v[94:95], v[204:205] op_sel_hi:[1,0]
	v_pk_mul_f32 v[84:85], v[84:85], v[204:205] op_sel_hi:[1,0]
	v_pk_mul_f32 v[86:87], v[86:87], v[204:205] op_sel_hi:[1,0]
	v_pk_mul_f32 v[76:77], v[76:77], v[206:207] op_sel_hi:[1,0]
	v_pk_mul_f32 v[78:79], v[78:79], v[206:207] op_sel_hi:[1,0]
	v_pk_mul_f32 v[68:69], v[68:69], v[206:207] op_sel_hi:[1,0]
	v_pk_mul_f32 v[70:71], v[70:71], v[206:207] op_sel_hi:[1,0]
	v_pk_mul_f32 v[88:89], v[88:89], v[204:205] op_sel_hi:[1,0]
	v_pk_mul_f32 v[90:91], v[90:91], v[204:205] op_sel_hi:[1,0]
	v_pk_mul_f32 v[80:81], v[80:81], v[204:205] op_sel_hi:[1,0]
	v_pk_mul_f32 v[82:83], v[82:83], v[204:205] op_sel_hi:[1,0]
	v_pk_mul_f32 v[72:73], v[72:73], v[206:207] op_sel_hi:[1,0]
	v_pk_mul_f32 v[74:75], v[74:75], v[206:207] op_sel_hi:[1,0]
	v_pk_mul_f32 v[64:65], v[64:65], v[206:207] op_sel_hi:[1,0]
	v_pk_mul_f32 v[66:67], v[66:67], v[206:207] op_sel_hi:[1,0]
	v_pk_mul_f32 v[88:89], v[92:93], v[88:89]
	v_pk_mul_f32 v[90:91], v[94:95], v[90:91]
	v_pk_mul_f32 v[80:81], v[84:85], v[80:81]
	v_pk_mul_f32 v[82:83], v[86:87], v[82:83]
	v_pk_mul_f32 v[72:73], v[76:77], v[72:73]
	v_pk_mul_f32 v[74:75], v[78:79], v[74:75]
	v_pk_mul_f32 v[64:65], v[68:69], v[64:65]
	v_pk_mul_f32 v[66:67], v[70:71], v[66:67]
	v_pk_mul_f32 v[92:93], v[92:93], v[134:135] op_sel_hi:[1,0]
	v_pk_mul_f32 v[94:95], v[94:95], v[134:135] op_sel_hi:[1,0]
	v_pk_mul_f32 v[84:85], v[84:85], v[134:135] op_sel_hi:[1,0]
	v_pk_mul_f32 v[86:87], v[86:87], v[134:135] op_sel_hi:[1,0]
	v_pk_mul_f32 v[76:77], v[76:77], v[134:135] op_sel_hi:[1,0]
	v_pk_mul_f32 v[78:79], v[78:79], v[134:135] op_sel_hi:[1,0]
	v_pk_mul_f32 v[68:69], v[68:69], v[134:135] op_sel_hi:[1,0]
	v_pk_mul_f32 v[70:71], v[70:71], v[134:135] op_sel_hi:[1,0]
	v_exp_f32_e32 v92, v92
	v_exp_f32_e32 v93, v93
	v_exp_f32_e32 v94, v94
	v_exp_f32_e32 v95, v95
	v_exp_f32_e32 v84, v84
	v_exp_f32_e32 v85, v85
	v_exp_f32_e32 v86, v86
	v_exp_f32_e32 v87, v87
	v_exp_f32_e32 v76, v76
	v_exp_f32_e32 v77, v77
	v_exp_f32_e32 v78, v78
	v_exp_f32_e32 v79, v79
	v_exp_f32_e32 v68, v68
	v_exp_f32_e32 v69, v69
	v_exp_f32_e32 v70, v70
	v_exp_f32_e32 v71, v71
	v_pk_add_f32 v[92:93], v[92:93], v[128:129]
	v_pk_add_f32 v[94:95], v[94:95], v[128:129]
	v_pk_add_f32 v[84:85], v[84:85], v[128:129]
	v_pk_add_f32 v[86:87], v[86:87], v[128:129]
	v_pk_add_f32 v[76:77], v[76:77], v[128:129]
	v_pk_add_f32 v[78:79], v[78:79], v[128:129]
	v_pk_add_f32 v[68:69], v[68:69], v[128:129]
	v_pk_add_f32 v[70:71], v[70:71], v[128:129]
	v_rcp_f32_e32 v92, v92
	v_rcp_f32_e32 v93, v93
	v_rcp_f32_e32 v94, v94
	v_rcp_f32_e32 v95, v95
	v_rcp_f32_e32 v84, v84
	v_rcp_f32_e32 v85, v85
	v_rcp_f32_e32 v86, v86
	v_rcp_f32_e32 v87, v87
	v_rcp_f32_e32 v76, v76
	v_rcp_f32_e32 v77, v77
	v_rcp_f32_e32 v78, v78
	v_rcp_f32_e32 v79, v79
	v_rcp_f32_e32 v68, v68
	v_rcp_f32_e32 v69, v69
	v_rcp_f32_e32 v70, v70
	v_rcp_f32_e32 v71, v71
	v_pk_mul_f32 v[88:89], v[88:89], v[92:93]
	v_pk_mul_f32 v[90:91], v[90:91], v[94:95]
	v_pk_mul_f32 v[80:81], v[80:81], v[84:85]
	v_pk_mul_f32 v[82:83], v[82:83], v[86:87]
	v_pk_mul_f32 v[72:73], v[72:73], v[76:77]
	v_pk_mul_f32 v[74:75], v[74:75], v[78:79]
	v_pk_mul_f32 v[64:65], v[64:65], v[68:69]
	v_pk_mul_f32 v[66:67], v[66:67], v[70:71]
	v_cvt_pk_bf16_f32 v92, v88, v89
	v_cvt_pk_bf16_f32 v93, v90, v91
	v_cvt_pk_bf16_f32 v94, v80, v81
	v_cvt_pk_bf16_f32 v95, v82, v83
	v_cvt_pk_bf16_f32 v76, v72, v73
	v_cvt_pk_bf16_f32 v77, v74, v75
	v_cvt_pk_bf16_f32 v78, v64, v65
	v_cvt_pk_bf16_f32 v79, v66, v67
	v_add_u32_e32 v138, 0x2c000, v132
	global_store_dwordx4 v138, v[92:95], s[8:9] sc1
	v_add_u32_e32 v139, 0x42000, v132
	global_store_dwordx4 v139, v[76:79], s[8:9] sc1
	v_pk_mul_f32 v[60:61], v[60:61], v[208:209] op_sel_hi:[1,0]
	v_pk_mul_f32 v[62:63], v[62:63], v[208:209] op_sel_hi:[1,0]
	v_pk_mul_f32 v[52:53], v[52:53], v[208:209] op_sel_hi:[1,0]
	v_pk_mul_f32 v[54:55], v[54:55], v[208:209] op_sel_hi:[1,0]
	v_pk_mul_f32 v[44:45], v[44:45], v[210:211] op_sel_hi:[1,0]
	v_pk_mul_f32 v[46:47], v[46:47], v[210:211] op_sel_hi:[1,0]
; __device__ __forceinline__ unsigned pk2(float lo, float hi) { return pg8::cvt_pk_bf16(lo, hi); }
; __device__ __forceinline__ float siluf_(float x) { return x * sigmoidf_(x); }
;     __device__ __forceinline__ void operator()(const f32x4 (&acc)[2][2][4][2], const pg8::Unit& u, int wr, int wc, int fr, int fq) const {
;     ...
;             for (int m = 0; m < 4; ++m) {
;                 const int row = row0 + ai * 128 + m * 16; const float r = rs[ai * 4 + m];
;                 float h[8];
; #pragma unroll
;                 for (int n = 0; n < 2; ++n)
; #pragma unroll
;                     for (int j = 0; j < 4; ++j) { const float g = acc[ai][0][m][n][j] * r, up = acc[ai][1][m][n][j] * r; h[n * 4 + j] = siluf_(g) * up; }
;                 u32x4 w; w.x = pk2(h[0], h[1]); w.y = pk2(h[2], h[3]); w.z = pk2(h[4], h[5]); w.w = pk2(h[6], h[7]);
;                 *(u32x4*)(H + (size_t)row * FF + col0) = w;
	v_pk_mul_f32 v[36:37], v[36:37], v[210:211] op_sel_hi:[1,0]
	v_pk_mul_f32 v[38:39], v[38:39], v[210:211] op_sel_hi:[1,0]
	v_pk_mul_f32 v[56:57], v[56:57], v[208:209] op_sel_hi:[1,0]
	v_pk_mul_f32 v[58:59], v[58:59], v[208:209] op_sel_hi:[1,0]
	v_pk_mul_f32 v[48:49], v[48:49], v[208:209] op_sel_hi:[1,0]
	v_pk_mul_f32 v[50:51], v[50:51], v[208:209] op_sel_hi:[1,0]
	v_pk_mul_f32 v[40:41], v[40:41], v[210:211] op_sel_hi:[1,0]
	v_pk_mul_f32 v[42:43], v[42:43], v[210:211] op_sel_hi:[1,0]
	v_pk_mul_f32 v[32:33], v[32:33], v[210:211] op_sel_hi:[1,0]
	v_pk_mul_f32 v[34:35], v[34:35], v[210:211] op_sel_hi:[1,0]
	v_pk_mul_f32 v[56:57], v[60:61], v[56:57]
	v_pk_mul_f32 v[58:59], v[62:63], v[58:59]
	v_pk_mul_f32 v[48:49], v[52:53], v[48:49]
	v_pk_mul_f32 v[50:51], v[54:55], v[50:51]
	v_pk_mul_f32 v[40:41], v[44:45], v[40:41]
	v_pk_mul_f32 v[42:43], v[46:47], v[42:43]
	v_pk_mul_f32 v[32:33], v[36:37], v[32:33]
	v_pk_mul_f32 v[34:35], v[38:39], v[34:35]
	v_pk_mul_f32 v[60:61], v[60:61], v[134:135] op_sel_hi:[1,0]
	v_pk_mul_f32 v[62:63], v[62:63], v[134:135] op_sel_hi:[1,0]
	v_pk_mul_f32 v[52:53], v[52:53], v[134:135] op_sel_hi:[1,0]
	v_pk_mul_f32 v[54:55], v[54:55], v[134:135] op_sel_hi:[1,0]
	v_pk_mul_f32 v[44:45], v[44:45], v[134:135] op_sel_hi:[1,0]
	v_pk_mul_f32 v[46:47], v[46:47], v[134:135] op_sel_hi:[1,0]
	v_pk_mul_f32 v[36:37], v[36:37], v[134:135] op_sel_hi:[1,0]
	v_pk_mul_f32 v[38:39], v[38:39], v[134:135] op_sel_hi:[1,0]
	v_exp_f32_e32 v60, v60
	v_exp_f32_e32 v61, v61
	v_exp_f32_e32 v62, v62
	v_exp_f32_e32 v63, v63
	v_exp_f32_e32 v52, v52
	v_exp_f32_e32 v53, v53
	v_exp_f32_e32 v54, v54
	v_exp_f32_e32 v55, v55
	v_exp_f32_e32 v44, v44
	v_exp_f32_e32 v45, v45
	v_exp_f32_e32 v46, v46
	v_exp_f32_e32 v47, v47
	v_exp_f32_e32 v36, v36
	v_exp_f32_e32 v37, v37
	v_exp_f32_e32 v38, v38
	v_exp_f32_e32 v39, v39
	v_pk_add_f32 v[60:61], v[60:61], v[128:129]
	v_pk_add_f32 v[62:63], v[62:63], v[128:129]
	v_pk_add_f32 v[52:53], v[52:53], v[128:129]
	v_pk_add_f32 v[54:55], v[54:55], v[128:129]
	v_pk_add_f32 v[44:45], v[44:45], v[128:129]
	v_pk_add_f32 v[46:47], v[46:47], v[128:129]
	v_pk_add_f32 v[36:37], v[36:37], v[128:129]
	v_pk_add_f32 v[38:39], v[38:39], v[128:129]
	v_rcp_f32_e32 v60, v60
	v_rcp_f32_e32 v61, v61
	v_rcp_f32_e32 v62, v62
	v_rcp_f32_e32 v63, v63
	v_rcp_f32_e32 v52, v52
	v_rcp_f32_e32 v53, v53
	v_rcp_f32_e32 v54, v54
	v_rcp_f32_e32 v55, v55
	v_rcp_f32_e32 v44, v44
	v_rcp_f32_e32 v45, v45
	v_rcp_f32_e32 v46, v46
	v_rcp_f32_e32 v47, v47
	v_rcp_f32_e32 v36, v36
	v_rcp_f32_e32 v37, v37
	v_rcp_f32_e32 v38, v38
	v_rcp_f32_e32 v39, v39
	v_pk_mul_f32 v[56:57], v[56:57], v[60:61]
	v_pk_mul_f32 v[58:59], v[58:59], v[62:63]
	v_pk_mul_f32 v[48:49], v[48:49], v[52:53]
	v_pk_mul_f32 v[50:51], v[50:51], v[54:55]
	v_pk_mul_f32 v[40:41], v[40:41], v[44:45]
	v_pk_mul_f32 v[42:43], v[42:43], v[46:47]
	v_pk_mul_f32 v[32:33], v[32:33], v[36:37]
	v_pk_mul_f32 v[34:35], v[34:35], v[38:39]
	v_cvt_pk_bf16_f32 v60, v56, v57
	v_cvt_pk_bf16_f32 v61, v58, v59
	v_cvt_pk_bf16_f32 v62, v48, v49
	v_cvt_pk_bf16_f32 v63, v50, v51
	v_cvt_pk_bf16_f32 v44, v40, v41
	v_cvt_pk_bf16_f32 v45, v42, v43
	v_cvt_pk_bf16_f32 v46, v32, v33
	v_cvt_pk_bf16_f32 v47, v34, v35
	v_add_u32_e32 v140, 0xb0000, v132
	global_store_dwordx4 v140, v[60:63], s[8:9] sc1
	v_add_u32_e32 v141, 0xc6000, v132
	global_store_dwordx4 v141, v[44:47], s[8:9] sc1
	v_pk_mul_f32 v[28:29], v[28:29], v[212:213] op_sel_hi:[1,0]
	v_pk_mul_f32 v[30:31], v[30:31], v[212:213] op_sel_hi:[1,0]
	v_pk_mul_f32 v[20:21], v[20:21], v[212:213] op_sel_hi:[1,0]
	v_pk_mul_f32 v[22:23], v[22:23], v[212:213] op_sel_hi:[1,0]
; #define PG8_BAR __builtin_amdgcn_s_barrier()
; __device__ __forceinline__ unsigned pk2(float lo, float hi) { return pg8::cvt_pk_bf16(lo, hi); }
; __device__ __forceinline__ float siluf_(float x) { return x * sigmoidf_(x); }
; template <class Epi, class Sched, bool ALIGN_EPI = false, bool SP2 = false>
; __device__ __forceinline__ void gemm_phase(PG8_LAS unsigned char* lds, const Gemm g, const Sched& S, const Epi& E) {
;     ...
;         if constexpr (ALIGN_EPI) { if (wr == 0) PG8_BAR; }
;         if constexpr (!Epi::AFTER_DRAIN) { E(acc, cur, wr, wc, fr, fq); S.done(cur); }
;         if (!has_next) break;
;     __device__ __forceinline__ void operator()(const f32x4 (&acc)[2][2][4][2], const pg8::Unit& u, int wr, int wc, int fr, int fq) const {
;     ...
;             for (int m = 0; m < 4; ++m) {
;                 const int row = row0 + ai * 128 + m * 16; const float r = rs[ai * 4 + m];
;                 float h[8];
; #pragma unroll
;                 for (int n = 0; n < 2; ++n)
; #pragma unroll
;                     for (int j = 0; j < 4; ++j) { const float g = acc[ai][0][m][n][j] * r, up = acc[ai][1][m][n][j] * r; h[n * 4 + j] = siluf_(g) * up; }
;                 u32x4 w; w.x = pk2(h[0], h[1]); w.y = pk2(h[2], h[3]); w.z = pk2(h[4], h[5]); w.w = pk2(h[6], h[7]);
;                 *(u32x4*)(H + (size_t)row * FF + col0) = w;
	v_pk_mul_f32 v[12:13], v[12:13], v[214:215] op_sel_hi:[1,0]
	v_pk_mul_f32 v[14:15], v[14:15], v[214:215] op_sel_hi:[1,0]
	v_pk_mul_f32 v[4:5], v[4:5], v[214:215] op_sel_hi:[1,0]
	v_pk_mul_f32 v[6:7], v[6:7], v[214:215] op_sel_hi:[1,0]
	v_pk_mul_f32 v[24:25], v[24:25], v[212:213] op_sel_hi:[1,0]
	v_pk_mul_f32 v[26:27], v[26:27], v[212:213] op_sel_hi:[1,0]
	v_pk_mul_f32 v[16:17], v[16:17], v[212:213] op_sel_hi:[1,0]
	v_pk_mul_f32 v[18:19], v[18:19], v[212:213] op_sel_hi:[1,0]
	v_pk_mul_f32 v[8:9], v[8:9], v[214:215] op_sel_hi:[1,0]
	v_pk_mul_f32 v[10:11], v[10:11], v[214:215] op_sel_hi:[1,0]
	v_pk_mul_f32 v[0:1], v[0:1], v[214:215] op_sel_hi:[1,0]
	v_pk_mul_f32 v[2:3], v[2:3], v[214:215] op_sel_hi:[1,0]
	v_pk_mul_f32 v[24:25], v[28:29], v[24:25]
	v_pk_mul_f32 v[26:27], v[30:31], v[26:27]
	v_pk_mul_f32 v[16:17], v[20:21], v[16:17]
	v_pk_mul_f32 v[18:19], v[22:23], v[18:19]
	v_pk_mul_f32 v[8:9], v[12:13], v[8:9]
	v_pk_mul_f32 v[10:11], v[14:15], v[10:11]
	v_pk_mul_f32 v[0:1], v[4:5], v[0:1]
	v_pk_mul_f32 v[2:3], v[6:7], v[2:3]
	v_pk_mul_f32 v[28:29], v[28:29], v[134:135] op_sel_hi:[1,0]
	v_pk_mul_f32 v[30:31], v[30:31], v[134:135] op_sel_hi:[1,0]
	v_pk_mul_f32 v[20:21], v[20:21], v[134:135] op_sel_hi:[1,0]
	v_pk_mul_f32 v[22:23], v[22:23], v[134:135] op_sel_hi:[1,0]
	v_pk_mul_f32 v[12:13], v[12:13], v[134:135] op_sel_hi:[1,0]
	v_pk_mul_f32 v[14:15], v[14:15], v[134:135] op_sel_hi:[1,0]
	v_pk_mul_f32 v[4:5], v[4:5], v[134:135] op_sel_hi:[1,0]
	v_pk_mul_f32 v[6:7], v[6:7], v[134:135] op_sel_hi:[1,0]
	v_exp_f32_e32 v28, v28
	v_exp_f32_e32 v29, v29
	v_exp_f32_e32 v30, v30
	v_exp_f32_e32 v31, v31
	v_exp_f32_e32 v20, v20
	v_exp_f32_e32 v21, v21
	v_exp_f32_e32 v22, v22
	v_exp_f32_e32 v23, v23
	v_exp_f32_e32 v12, v12
	v_exp_f32_e32 v13, v13
	v_exp_f32_e32 v14, v14
	v_exp_f32_e32 v15, v15
	v_exp_f32_e32 v4, v4
	v_exp_f32_e32 v5, v5
	v_exp_f32_e32 v6, v6
	v_exp_f32_e32 v7, v7
	v_pk_add_f32 v[28:29], v[28:29], v[128:129]
	v_pk_add_f32 v[30:31], v[30:31], v[128:129]
	v_pk_add_f32 v[20:21], v[20:21], v[128:129]
	v_pk_add_f32 v[22:23], v[22:23], v[128:129]
	v_pk_add_f32 v[12:13], v[12:13], v[128:129]
	v_pk_add_f32 v[14:15], v[14:15], v[128:129]
	v_pk_add_f32 v[4:5], v[4:5], v[128:129]
	v_pk_add_f32 v[6:7], v[6:7], v[128:129]
	v_rcp_f32_e32 v28, v28
	v_rcp_f32_e32 v29, v29
	v_rcp_f32_e32 v30, v30
	v_rcp_f32_e32 v31, v31
	v_rcp_f32_e32 v20, v20
	v_rcp_f32_e32 v21, v21
	v_rcp_f32_e32 v22, v22
	v_rcp_f32_e32 v23, v23
	v_rcp_f32_e32 v12, v12
	v_rcp_f32_e32 v13, v13
	v_rcp_f32_e32 v14, v14
	v_rcp_f32_e32 v15, v15
	v_rcp_f32_e32 v4, v4
	v_rcp_f32_e32 v5, v5
	v_rcp_f32_e32 v6, v6
	v_rcp_f32_e32 v7, v7
	v_pk_mul_f32 v[24:25], v[24:25], v[28:29]
	v_pk_mul_f32 v[26:27], v[26:27], v[30:31]
	v_pk_mul_f32 v[16:17], v[16:17], v[20:21]
	v_pk_mul_f32 v[18:19], v[18:19], v[22:23]
	v_pk_mul_f32 v[8:9], v[8:9], v[12:13]
	v_pk_mul_f32 v[10:11], v[10:11], v[14:15]
	v_pk_mul_f32 v[0:1], v[0:1], v[4:5]
	v_pk_mul_f32 v[2:3], v[2:3], v[6:7]
	v_cvt_pk_bf16_f32 v28, v24, v25
	v_cvt_pk_bf16_f32 v29, v26, v27
	v_cvt_pk_bf16_f32 v30, v16, v17
	v_cvt_pk_bf16_f32 v31, v18, v19
	v_cvt_pk_bf16_f32 v12, v8, v9
	v_cvt_pk_bf16_f32 v13, v10, v11
	v_cvt_pk_bf16_f32 v14, v0, v1
	v_cvt_pk_bf16_f32 v15, v2, v3
	v_add_u32_e32 v142, 0xdc000, v132
	global_store_dwordx4 v142, v[28:31], s[8:9] sc1
	v_add_u32_e32 v143, 0xf2000, v132
	global_store_dwordx4 v143, v[12:15], s[8:9] sc1
	s_andn2_b64 vcc, exec, s[36:37]
	s_mov_b64 s[0:1], -1
	s_cbranch_vccnz .LBB0_1643
	s_andn2_b64 vcc, exec, s[40:41]
	s_cbranch_vccnz .LBB0_1642
	s_barrier
	s_branch .LBB0_1642
